# diff-attention steady loop: fewer VALU (running load pointers, max3 trees, exit-only phi copies, partial-max ballot) on top of norm+prologue edits
# speedup vs baseline: 1.0161x; 1.0161x over previous
; template <int NMAP, int VD, bool SWA> ...
;     ...
;     { const bf16_t* qr = Qp + (size_t)(16 * w + fr) * qpitch + fq * 8;
; #pragma unroll
;       for (int mp = 0; mp < NMAP; ++mp)
; #pragma unroll
;           for (int ks = 0; ks < 2; ++ks) qf[mp][ks] = *(const bf16x8*)(qr + mp * 64 + ks * 32); }
;     f32x4 oacc[NMAP][NET], negm[NMAP]; float mrun[NMAP], lsum[NMAP];
; #pragma unroll
;     for (int mp = 0; mp < NMAP; ++mp) { mrun[mp] = 0.f; lsum[mp] = 0.f; negm[mp] = (f32x4){0.f, 0.f, 0.f, 0.f};
; #pragma unroll
;         for (int et = 0; et < NET; ++et) oacc[mp][et] = (f32x4){0.f, 0.f, 0.f, 0.f}; }
;     const int ntiles = n0 + (t1hi - t1lo);
;     u32x4 kreg[NKC], vreg[NVC];
;     ...
;     ATT_LOAD(ATT_TILE(0));
;     ATT_STORE(0);
;     if (ntiles > 1) ATT_LOAD(ATT_TILE(1));
;     __syncthreads();
; __device__ __forceinline__ void mix_phase(const Args& a, LAS unsigned char* lds, int l, int tid_in, int G) {
;     ...
;         if (u < e3) {
;             const bool is_swa = (u >= e0 && u < e1) || (u >= e2);
;             const bool is_ctx = (u >= e1);
;             int b, hh, qb, row0;
;             if (u < e0) {
;                 const int v = u, x = v & 7, slot = (v >> 3) & 31, rnd = v >> 8, P = x * 4 + rnd * 2 + (slot >> 4);
;                 b = P >> 2; hh = P & 3; qb = slot & 15; row0 = b * SEQ + 128 * qb; }
;             else if (u < e1) { const int v = u - e0, x = v & 7, slot = (v >> 3) & 31, P = x * 2 + (slot >> 4); b = P >> 1; hh = P & 1; qb = slot & 15; row0 = b * SEQ + 128 * qb; }
;             else if (u < e2) { const int v = u - e1; b = v >> 3; hh = (v >> 1) & 3; qb = v & 1; row0 = T_LAT + b * CTXL + 128 * qb; }
;             else { const int v = u - e2; b = v >> 2; hh = (v >> 1) & 1; qb = v & 1; row0 = T_LAT + b * CTXL + 128 * qb; }
;             if (!is_swa) {
;                 attn_unit<2, 128, false>(lds, QB + (size_t)row0 * 512 + hh * 128, 512, KB + (size_t)(b * 4 + hh) * NKEY * 128, VBt + (size_t)(b * 4 + hh) * NKEY * 128,
;                                          is_ctx ? 4 : 36, 0, 0, 0, 0.f, lam, gsub, post_scale, O + (size_t)row0 * DM + 256 + hh * 128, tid);
.LBB0_121:
	s_and_b32 s0, s22, 0xffffff00
	s_cmpk_eq_i32 s0, 0x200
	s_cselect_b64 s[0:1], -1, 0
	s_cmp_ge_i32 s22, s13
	s_cselect_b64 s[8:9], -1, 0
	s_or_b64 s[10:11], s[8:9], s[0:1]
	s_cmpk_gt_i32 s22, 0x2ff
	s_mov_b64 s[8:9], -1
	s_cselect_b64 s[0:1], -1, 0
	s_and_b64 vcc, exec, s[10:11]
	v_ashrrev_i32_e32 v178, 31, v176
	v_lshlrev_b32_e32 v175, 2, v177
	s_cbranch_vccnz .LBB0_139
	s_ashr_i32 s21, s20, 31
	s_lshl_b64 s[8:9], s[20:21], 10
	v_readlane_b32 s3, v252, 43
	s_add_u32 s3, s3, s8
	v_readlane_b32 s8, v252, 44
	s_addc_u32 s8, s8, s9
	s_lshl_b32 s25, s16, 7
	s_lshl_b32 s9, s16, 8
	s_waitcnt vmcnt(0) lgkmcnt(0)
	v_add_u32_e32 v22, 0x200, v176
	s_add_u32 s28, s3, s9
	v_lshrrev_b32_e32 v0, 28, v178
	v_ashrrev_i32_e32 v23, 31, v22
	s_addc_u32 s29, s8, 0
	s_lshl_b32 s14, s24, 2
	v_add_u32_e32 v0, v176, v0
	v_lshrrev_b32_e32 v23, 28, v23
	s_add_i32 s14, s14, s16
	v_ashrrev_i32_e32 v34, 4, v0
	v_add_u32_e32 v23, v22, v23
	s_mul_i32 s8, s14, 0x90000
	v_readlane_b32 s9, v252, 47
	v_and_b32_e32 v0, -16, v0
	v_ashrrev_i32_e32 v35, 31, v34
	v_ashrrev_i32_e32 v36, 4, v23
	v_and_b32_e32 v23, -16, v23
	s_mul_hi_i32 s3, s14, 0x90000
	s_add_u32 s10, s9, s8
	v_readlane_b32 s9, v252, 48
	v_sub_u32_e32 v0, v176, v0
	v_lshlrev_b64 v[58:59], 8, v[34:35]
	v_sub_u32_e32 v35, v22, v23
	s_addc_u32 s11, s9, s3
	v_readlane_b32 s9, v252, 49
	v_ashrrev_i32_e32 v161, 31, v160
	v_lshlrev_b32_e32 v20, 3, v0
	v_ashrrev_i32_e32 v37, 31, v36
	v_lshlrev_b32_e32 v24, 3, v35
	s_add_u32 s8, s9, s8
	v_readlane_b32 s9, v252, 50
	v_lshlrev_b64 v[2:3], 10, v[160:161]
	v_ashrrev_i32_e32 v21, 31, v20
	v_lshlrev_b64 v[94:95], 8, v[36:37]
	v_ashrrev_i32_e32 v25, 31, v24
	s_addc_u32 s9, s9, s3
	v_lshl_add_u64 v[2:3], s[28:29], 0, v[2:3]
	v_mov_b32_e32 v163, v1
	v_lshl_add_u64 v[18:19], s[10:11], 0, v[58:59]
	v_lshlrev_b64 v[60:61], 1, v[20:21]
	v_lshl_add_u64 v[22:23], s[10:11], 0, v[94:95]
	v_lshlrev_b64 v[96:97], 1, v[24:25]
	v_lshl_add_u64 v[2:3], v[2:3], 0, v[162:163]
	v_lshl_add_u64 v[18:19], v[18:19], 0, v[60:61]
	v_lshl_add_u64 v[22:23], v[22:23], 0, v[96:97]
	v_lshl_add_u64 v[26:27], s[8:9], 0, v[58:59]
	global_load_dwordx4 v[14:17], v[2:3], off
	global_load_dwordx4 v[10:13], v[2:3], off offset:64
	global_load_dwordx4 v[6:9], v[2:3], off offset:128
	s_nop 0
	global_load_dwordx4 v[2:5], v[2:3], off offset:192
	v_lshl_add_u64 v[26:27], v[26:27], 0, v[60:61]
	global_load_dwordx4 v[18:21], v[18:19], off
	v_lshl_add_u64 v[30:31], s[8:9], 0, v[94:95]
	global_load_dwordx4 v[22:25], v[22:23], off
	v_lshl_add_u64 v[30:31], v[30:31], 0, v[96:97]
	global_load_dwordx4 v[26:29], v[26:27], off
	s_movk_i32 s15, 0x120
	global_load_dwordx4 v[30:33], v[30:31], off
	v_mul_lo_u32 v208, v34, s15
	v_lshlrev_b32_e32 v209, 4, v0
	v_mul_lo_u32 v210, v36, s15
	v_lshlrev_b32_e32 v211, 4, v35
	v_add3_u32 v34, 0, v208, v209
	v_add3_u32 v35, 0, v210, v211
	s_mov_b64 s[34:35], 0x4000
	v_lshlrev_b32_e32 v36, 2, v176
	v_and_b32_e32 v56, 12, v36
	v_mbcnt_hi_u32_b32 v36, -1, v190
	v_and_b32_e32 v38, 64, v36
	v_xor_b32_e32 v37, 16, v36
	v_add_u32_e32 v38, 64, v38
	v_cmp_lt_i32_e32 vcc, v37, v38
	v_mul_u32_u24_e32 v182, 0x120, v173
	v_add3_u32 v57, 0, v162, v182
	v_cndmask_b32_e32 v37, v36, v37, vcc
	v_lshlrev_b32_e32 v179, 2, v37
	v_xor_b32_e32 v37, 32, v36
	v_cmp_lt_i32_e32 vcc, v37, v38
	v_readlane_b32 s28, v254, 39
	v_readlane_b32 s29, v254, 40
	v_cndmask_b32_e32 v36, v36, v37, vcc
	v_lshlrev_b32_e32 v180, 2, v36
	v_lshlrev_b32_e32 v163, 2, v177
	v_bfe_u32 v0, v176, 2, 2
	s_mov_b32 s26, s28
	v_readlane_b32 s28, v254, 43
	v_or_b32_e32 v0, v163, v0
	v_readlane_b32 s29, v254, 44
	v_lshlrev_b32_e32 v107, 3, v177
	s_mov_b32 s3, 1
	v_mul_u32_u24_e32 v0, 0x120, v0
	s_waitcnt vmcnt(3)
	ds_write_b128 v34, v[18:21]
	s_waitcnt vmcnt(2)
	ds_write_b128 v35, v[22:25]
	s_waitcnt vmcnt(1)
	ds_write_b128 v34, v[26:29] offset:18432
	s_waitcnt vmcnt(0)
	ds_write_b128 v35, v[30:33] offset:18432
	v_lshl_add_u64 v[26:27], v[58:59], 0, s[34:35]
	v_lshl_add_u64 v[18:19], s[10:11], 0, v[26:27]
	v_lshl_add_u64 v[30:31], v[94:95], 0, s[34:35]
	v_lshl_add_u64 v[18:19], v[18:19], 0, v[60:61]
	v_lshl_add_u64 v[22:23], s[10:11], 0, v[30:31]
	global_load_dwordx4 v[18:21], v[18:19], off
	v_lshl_add_u64 v[22:23], v[22:23], 0, v[96:97]
	v_lshl_add_u64 v[26:27], s[8:9], 0, v[26:27]
	global_load_dwordx4 v[22:25], v[22:23], off
	v_lshl_add_u64 v[26:27], v[26:27], 0, v[60:61]
	v_lshl_add_u64 v[30:31], s[8:9], 0, v[30:31]
	global_load_dwordx4 v[26:29], v[26:27], off
	v_lshl_add_u64 v[30:31], v[30:31], 0, v[96:97]
	global_load_dwordx4 v[30:33], v[30:31], off
	s_mov_b64 s[34:35], 0x8000
	s_waitcnt lgkmcnt(0)
	s_barrier
; #define LAS __attribute__((address_space(3)))
; template <int NMAP, int VD, bool SWA> ...
;     ...
;     for (int i = 0; i < ntiles; ++i) {
;         const int t = ATT_TILE(i);
;         if (i + 1 < ntiles) { ATT_STORE((i + 1) & 1); if (i + 2 < ntiles) ATT_LOAD(ATT_TILE(i + 2)); }
;         const LAS bf16_t* kS = (const LAS bf16_t*)(lds + (i & 1) * BUFB);
;         const LAS bf16_t* vS = (const LAS bf16_t*)(lds + (i & 1) * BUFB + KBYTES);
;         bf16x8 pf[NMAP][2];
;         f32x4 sacc[NMAP][4];
; #pragma unroll
;         for (int mp = 0; mp < NMAP; ++mp) {
;             bf16x8 kf[4][2];
; #pragma unroll
;             for (int kt = 0; kt < 4; ++kt)
; #pragma unroll
;                 for (int ks = 0; ks < 2; ++ks) kf[kt][ks] = *(const LAS bf16x8*)(kS + (16 * kt + fr) * KP + mp * KMS + ks * 32 + fq * 8);
;             __builtin_amdgcn_sched_barrier(0);
; #pragma unroll
;             for (int kt = 0; kt < 4; ++kt) sacc[mp][kt] = __builtin_amdgcn_mfma_f32_16x16x32_bf16(kf[kt][0], qf[mp][0], negm[mp], 0, 0, 0);
; #pragma unroll
;             for (int kt = 0; kt < 4; ++kt) sacc[mp][kt] = __builtin_amdgcn_mfma_f32_16x16x32_bf16(kf[kt][1], qf[mp][1], sacc[mp][kt], 0, 0, 0);
;         }
;         bf16x8 va[4];
;     ...
; #pragma unroll
;         for (int i2 = 0; i2 < 4; ++i2) ATT_LDV(va[i2], i2);
;         if (SWA && t >= 4) {
;             const int dq = qp0 + 16 * w + fr - (64 * (t - 4) + 4 * fq);
; #pragma unroll
;             for (int kt = 0; kt < 4; ++kt)
; #pragma unroll
;                 for (int r = 0; r < 4; ++r) { const int d = dq - 16 * kt - r; if (d > 128 || d < -128) {
; #pragma unroll
;                     for (int mp = 0; mp < NMAP; ++mp) sacc[mp][kt][r] = -INFINITY; } }
;         }
;         float mx[NMAP];
; #pragma unroll
;         for (int mp = 0; mp < NMAP; ++mp) {
;             float v = fmax2(fmax2(sacc[mp][0][0], sacc[mp][0][1]), fmax2(sacc[mp][0][2], sacc[mp][0][3]));
; #pragma unroll
;             for (int kt = 1; kt < 4; ++kt) v = fmax2(v, fmax2(fmax2(sacc[mp][kt][0], sacc[mp][kt][1]), fmax2(sacc[mp][kt][2], sacc[mp][kt][3])));
;             mx[mp] = v;
;         }
; #pragma unroll
;         for (int mp = 0; mp < NMAP; ++mp) mx[mp] = fmax2(mx[mp], __shfl_xor(mx[mp], 16));
; #pragma unroll
;         for (int mp = 0; mp < NMAP; ++mp) mx[mp] = fmax2(mx[mp], __shfl_xor(mx[mp], 32));
; #pragma unroll
;         for (int mp = 0; mp < NMAP; ++mp) {
	s_waitcnt vmcnt(3)
	ds_write_b128 v34, v[18:21] offset:36864
	s_waitcnt vmcnt(2)
	ds_write_b128 v35, v[22:25] offset:36864
	s_waitcnt vmcnt(1)
	ds_write_b128 v34, v[26:29] offset:55296
	s_waitcnt vmcnt(0)
	ds_write_b128 v35, v[30:33] offset:55296
	v_lshl_add_u64 v[18:19], v[58:59], 0, s[34:35]
	v_lshl_add_u64 v[20:21], s[10:11], 0, v[18:19]
	v_lshl_add_u64 v[18:19], s[8:9], 0, v[18:19]
	v_lshl_add_u64 v[20:21], v[20:21], 0, v[60:61]
	v_lshl_add_u64 v[18:19], v[18:19], 0, v[60:61]
	global_load_dwordx4 v[86:89], v[20:21], off
	global_load_dwordx4 v[98:101], v[18:19], off
	v_lshl_add_u64 v[20:21], v[94:95], 0, s[34:35]
	v_lshl_add_u64 v[22:23], s[10:11], 0, v[20:21]
	v_lshl_add_u64 v[18:19], s[8:9], 0, v[20:21]
	v_lshl_add_u64 v[22:23], v[22:23], 0, v[96:97]
	v_lshl_add_u64 v[18:19], v[18:19], 0, v[96:97]
	global_load_dwordx4 v[90:93], v[22:23], off
	global_load_dwordx4 v[102:105], v[18:19], off
	ds_read_b128 v[18:21], v57
	ds_read_b128 v[22:25], v57 offset:64
	ds_read_b128 v[26:29], v57 offset:4608
	ds_read_b128 v[30:33], v57 offset:4672
	ds_read_b128 v[34:37], v57 offset:9216
	ds_read_b128 v[38:41], v57 offset:9280
	ds_read_b128 v[42:45], v57 offset:13824
	ds_read_b128 v[46:49], v57 offset:13888
	s_waitcnt lgkmcnt(7)
	v_mfma_f32_16x16x32_bf16 v[18:21], v[18:21], v[14:17], 0
	s_waitcnt lgkmcnt(5)
	v_mfma_f32_16x16x32_bf16 v[26:29], v[26:29], v[14:17], 0
	s_waitcnt lgkmcnt(3)
	v_mfma_f32_16x16x32_bf16 v[34:37], v[34:37], v[14:17], 0
	s_waitcnt lgkmcnt(1)
	v_mfma_f32_16x16x32_bf16 v[42:45], v[42:45], v[14:17], 0
	v_mfma_f32_16x16x32_bf16 v[18:21], v[22:25], v[10:13], v[18:21]
	v_mfma_f32_16x16x32_bf16 v[24:27], v[30:33], v[10:13], v[26:29]
	v_mfma_f32_16x16x32_bf16 v[28:31], v[38:41], v[10:13], v[34:37]
	s_waitcnt lgkmcnt(0)
	v_mfma_f32_16x16x32_bf16 v[32:35], v[46:49], v[10:13], v[42:45]
	s_nop 0
	ds_read_b128 v[36:39], v57 offset:128
	s_nop 0
	ds_read_b128 v[40:43], v57 offset:192
	ds_read_b128 v[44:47], v57 offset:4736
	ds_read_b128 v[48:51], v57 offset:4800
	ds_read_b128 v[52:55], v57 offset:9344
	ds_read_b128 v[62:65], v57 offset:9408
	ds_read_b128 v[66:69], v57 offset:13952
	ds_read_b128 v[70:73], v57 offset:14016
	v_lshlrev_b32_e32 v181, 1, v56
	v_med3_f32 v23, v18, v19, s27
	v_med3_f32 v56, v20, v21, s27
	s_waitcnt lgkmcnt(7)
	v_mfma_f32_16x16x32_bf16 v[36:39], v[36:39], v[6:9], 0
	v_med3_f32 v23, v23, v56, s27
	v_med3_f32 v56, v24, v25, s27
	v_med3_f32 v57, v26, v27, s27
	v_med3_f32 v56, v56, v57, s27
	s_waitcnt lgkmcnt(5)
	v_mfma_f32_16x16x32_bf16 v[44:47], v[44:47], v[6:9], 0
	v_med3_f32 v23, v23, v56, s27
	v_med3_f32 v56, v28, v29, s27
	v_med3_f32 v57, v30, v31, s27
	v_med3_f32 v56, v56, v57, s27
	v_med3_f32 v23, v23, v56, s27
	v_med3_f32 v56, v32, v33, s27
	v_mfma_f32_16x16x32_bf16 v[36:39], v[40:43], v[2:5], v[36:39]
	v_med3_f32 v40, v34, v35, s27
	v_med3_f32 v40, v56, v40, s27
	v_med3_f32 v23, v23, v40, s27
	s_waitcnt lgkmcnt(3)
	v_mfma_f32_16x16x32_bf16 v[52:55], v[52:55], v[6:9], 0
	v_add3_u32 v22, 0, v0, v181
	v_mad_i64_i32 v[58:59], s[8:9], s14, v192, v[58:59]
	v_mfma_f32_16x16x32_bf16 v[40:43], v[48:51], v[2:5], v[44:47]
	v_lshl_add_u64 v[58:59], v[58:59], 0, v[60:61]
	s_and_b64 s[8:9], s[0:1], exec
	s_cselect_b32 s10, 1, 33
	s_waitcnt lgkmcnt(1)
	v_mfma_f32_16x16x32_bf16 v[66:69], v[66:69], v[6:9], 0
	v_med3_f32 v44, v36, v37, s27
	v_med3_f32 v45, v38, v39, s27
	v_med3_f32 v56, v44, v45, s27
	v_mfma_f32_16x16x32_bf16 v[44:47], v[62:65], v[2:5], v[52:55]
	v_med3_f32 v48, v40, v41, s27
	v_med3_f32 v49, v42, v43, s27
	s_lshl_b32 s11, s10, 14
	v_med3_f32 v52, v48, v49, s27
	s_waitcnt lgkmcnt(0)
	v_mfma_f32_16x16x32_bf16 v[48:51], v[70:73], v[2:5], v[66:69]
	s_nop 1
	v_med3_f32 v53, v44, v45, s27
	v_med3_f32 v54, v46, v47, s27
	v_med3_f32 v52, v56, v52, s27
	v_med3_f32 v53, v53, v54, s27
	v_med3_f32 v52, v52, v53, s27
	s_nop 0
	v_med3_f32 v53, v48, v49, s27
	v_med3_f32 v54, v50, v51, s27
	v_med3_f32 v53, v53, v54, s27
	v_med3_f32 v54, v52, v53, s27
	ds_bpermute_b32 v55, v179, v23
	ds_bpermute_b32 v56, v179, v54
	ds_read_b64_tr_b16 v[52:53], v22 offset:18432
	ds_read_b64_tr_b16 v[62:63], v22 offset:18464
	ds_read_b64_tr_b16 v[66:67], v22 offset:18496
	ds_read_b64_tr_b16 v[70:71], v22 offset:18528
	s_waitcnt lgkmcnt(5)
	v_med3_f32 v23, v23, v55, s27
	s_waitcnt lgkmcnt(4)
	v_med3_f32 v56, v54, v56, s27
	ds_bpermute_b32 v57, v180, v23
	ds_bpermute_b32 v74, v180, v56
	ds_read_b64_tr_b16 v[54:55], v22 offset:23040
	ds_read_b64_tr_b16 v[64:65], v22 offset:23072
	ds_read_b64_tr_b16 v[68:69], v22 offset:23104
	ds_read_b64_tr_b16 v[72:73], v22 offset:23136
	s_waitcnt lgkmcnt(5)
	v_med3_f32 v23, v23, v57, s27
	s_waitcnt lgkmcnt(4)
	v_med3_f32 v109, v56, v74, s27
	v_sub_f32_e32 v35, v35, v23
	v_sub_f32_e32 v34, v34, v23
	v_sub_f32_e32 v33, v33, v23
	v_sub_f32_e32 v32, v32, v23
	v_sub_f32_e32 v31, v31, v23
	v_sub_f32_e32 v30, v30, v23
	v_sub_f32_e32 v29, v29, v23
	v_sub_f32_e32 v28, v28, v23
	v_sub_f32_e32 v27, v27, v23
	v_sub_f32_e32 v26, v26, v23
	v_sub_f32_e32 v25, v25, v23
	v_sub_f32_e32 v24, v24, v23
	v_sub_f32_e32 v21, v21, v23
	v_sub_f32_e32 v20, v20, v23
	v_sub_f32_e32 v19, v19, v23
	v_sub_f32_e32 v18, v18, v23
	v_exp_f32_e32 v111, v28
	v_exp_f32_e32 v156, v29
	v_exp_f32_e32 v157, v30
	v_exp_f32_e32 v164, v31
	v_exp_f32_e32 v165, v32
	v_exp_f32_e32 v166, v33
	v_exp_f32_e32 v167, v34
	v_exp_f32_e32 v183, v35
	v_sub_f32_e32 v28, v43, v109
	v_sub_f32_e32 v29, v42, v109
	v_sub_f32_e32 v30, v41, v109
	v_sub_f32_e32 v31, v40, v109
	v_sub_f32_e32 v32, v39, v109
	v_sub_f32_e32 v33, v38, v109
	v_sub_f32_e32 v34, v37, v109
	v_sub_f32_e32 v35, v36, v109
	v_exp_f32_e32 v56, v18
	v_exp_f32_e32 v57, v19
	v_exp_f32_e32 v74, v20
	v_exp_f32_e32 v75, v21
	v_exp_f32_e32 v76, v24
	v_exp_f32_e32 v106, v25
	v_exp_f32_e32 v108, v26
	v_exp_f32_e32 v110, v27
	v_cvt_pk_bf16_f32 v24, v56, v57
	v_cvt_pk_bf16_f32 v25, v74, v75
	v_cvt_pk_bf16_f32 v26, v76, v106
	v_cvt_pk_bf16_f32 v27, v108, v110
	v_cvt_pk_bf16_f32 v18, v111, v156
	v_cvt_pk_bf16_f32 v19, v157, v164
	v_cvt_pk_bf16_f32 v20, v165, v166
	v_cvt_pk_bf16_f32 v21, v167, v183
	v_sub_f32_e32 v77, v51, v109
	v_sub_f32_e32 v78, v50, v109
	v_sub_f32_e32 v79, v49, v109
	v_exp_f32_e32 v202, v35
	v_exp_f32_e32 v203, v34
	v_exp_f32_e32 v212, v33
	v_exp_f32_e32 v213, v32
	v_exp_f32_e32 v214, v31
	v_exp_f32_e32 v215, v30
	v_exp_f32_e32 v216, v29
	v_exp_f32_e32 v217, v28
	v_cvt_pk_bf16_f32 v28, v202, v203
	s_waitcnt lgkmcnt(3)
; __device__ __forceinline__ unsigned cvt_pk_bf16(float lo, float hi) { unsigned r; asm volatile("v_cvt_pk_bf16_f32 %0, %1, %2" : "=v"(r) : "v"(lo), "v"(hi)); return r; }
; template <int NMAP, int VD, bool SWA> ...
;     ...
;             float ps = 0.f;
; #pragma unroll
;             for (int kt = 0; kt < 4; ++kt)
; #pragma unroll
;                 for (int r = 0; r < 4; ++r) { const float p = __builtin_amdgcn_exp2f(sacc[mp][kt][r]); sacc[mp][kt][r] = p; ps += p; }
;             lsum[mp] += ps;
; #pragma unroll
;             for (int s2 = 0; s2 < 2; ++s2) {
;                 u32x4 pk; pk.x = cvt_pk_bf16(sacc[mp][2 * s2][0], sacc[mp][2 * s2][1]); pk.y = cvt_pk_bf16(sacc[mp][2 * s2][2], sacc[mp][2 * s2][3]);
;                 pk.z = cvt_pk_bf16(sacc[mp][2 * s2 + 1][0], sacc[mp][2 * s2 + 1][1]); pk.w = cvt_pk_bf16(sacc[mp][2 * s2 + 1][2], sacc[mp][2 * s2 + 1][3]);
;                 pf[mp][s2] = __builtin_bit_cast(bf16x8, pk);
;             }
;         }
; #pragma unroll
;         for (int idx = 0; idx < 2 * NET; ++idx) {
;             const int et = idx % NET, s2 = idx / NET;
;             const bf16x8 cur = va[idx & 3];
;             if (idx + 4 < 2 * NET) ATT_LDV(va[idx & 3], idx + 4);
; #pragma unroll
;             for (int mp = 0; mp < NMAP; ++mp) oacc[mp][et] = __builtin_amdgcn_mfma_f32_16x16x32_bf16(cur, pf[mp][s2], oacc[mp][et], 0, 0, 0);
;         }
	v_mfma_f32_16x16x32_bf16 v[32:35], v[52:55], v[24:27], 0
	v_cvt_pk_bf16_f32 v29, v212, v213
	v_cvt_pk_bf16_f32 v30, v214, v215
	v_cvt_pk_bf16_f32 v31, v216, v217
	v_sub_f32_e32 v49, v46, v109
	v_mfma_f32_16x16x32_bf16 v[36:39], v[52:55], v[28:31], 0
	v_sub_f32_e32 v52, v48, v109
	v_sub_f32_e32 v48, v47, v109
	v_sub_f32_e32 v50, v45, v109
	v_sub_f32_e32 v44, v44, v109
	s_waitcnt lgkmcnt(2)
	v_mfma_f32_16x16x32_bf16 v[40:43], v[62:65], v[24:27], 0
	v_exp_f32_e32 v218, v44
	v_exp_f32_e32 v219, v50
	v_exp_f32_e32 v220, v49
	v_mfma_f32_16x16x32_bf16 v[44:47], v[62:65], v[28:31], 0
	v_exp_f32_e32 v221, v48
	v_exp_f32_e32 v222, v52
	v_exp_f32_e32 v223, v79
	v_exp_f32_e32 v224, v78
	v_exp_f32_e32 v225, v77
	v_cvt_pk_bf16_f32 v112, v218, v219
	v_cvt_pk_bf16_f32 v113, v220, v221
	v_cvt_pk_bf16_f32 v114, v222, v223
	v_cvt_pk_bf16_f32 v115, v224, v225
	ds_read_b64_tr_b16 v[64:65], v22 offset:23168
	ds_read_b64_tr_b16 v[62:63], v22 offset:18560
	s_waitcnt lgkmcnt(3)
	v_mfma_f32_16x16x32_bf16 v[48:51], v[66:69], v[24:27], 0
	v_mfma_f32_16x16x32_bf16 v[52:55], v[66:69], v[28:31], 0
	ds_read_b64_tr_b16 v[68:69], v22 offset:23200
	ds_read_b64_tr_b16 v[66:67], v22 offset:18592
	s_waitcnt lgkmcnt(2)
	v_mfma_f32_16x16x32_bf16 v[124:127], v[62:65], v[24:27], 0
	v_mfma_f32_16x16x32_bf16 v[128:131], v[62:65], v[28:31], 0
	ds_read_b64_tr_b16 v[62:63], v22 offset:18624
	ds_read_b64_tr_b16 v[64:65], v22 offset:23232
	s_waitcnt lgkmcnt(2)
	v_mfma_f32_16x16x32_bf16 v[132:135], v[66:69], v[24:27], 0
	v_mfma_f32_16x16x32_bf16 v[136:139], v[66:69], v[28:31], 0
	ds_read_b64_tr_b16 v[66:67], v22 offset:18656
	s_waitcnt lgkmcnt(1)
	v_mfma_f32_16x16x32_bf16 v[140:143], v[62:65], v[24:27], 0
	v_mfma_f32_16x16x32_bf16 v[144:147], v[62:65], v[28:31], 0
	ds_read_b64_tr_b16 v[68:69], v22 offset:23264
	ds_read_b64_tr_b16 v[62:63], v22 offset:27648
	v_mfma_f32_16x16x32_bf16 v[116:119], v[70:73], v[24:27], 0
	s_waitcnt lgkmcnt(1)
	v_mfma_f32_16x16x32_bf16 v[148:151], v[66:69], v[24:27], 0
	ds_read_b64_tr_b16 v[64:65], v22 offset:32256
	ds_read_b64_tr_b16 v[24:25], v22 offset:27680
	ds_read_b64_tr_b16 v[152:153], v22 offset:27712
	s_waitcnt lgkmcnt(2)
	v_mfma_f32_16x16x32_bf16 v[78:81], v[62:65], v[18:21], v[32:35]
	s_nop 2
	v_add_f32_e32 v32, 0, v56
	v_add_f32_e32 v32, v57, v32
	v_add_f32_e32 v32, v74, v32
	v_add_f32_e32 v32, v75, v32
	v_mfma_f32_16x16x32_bf16 v[120:123], v[70:73], v[28:31], 0
	v_add_f32_e32 v32, v76, v32
	v_add_f32_e32 v32, v106, v32
	v_add_f32_e32 v32, v108, v32
	v_mfma_f32_16x16x32_bf16 v[168:171], v[66:69], v[28:31], 0
	ds_read_b64_tr_b16 v[28:29], v22 offset:27744
	ds_read_b64_tr_b16 v[26:27], v22 offset:32288
	ds_read_b64_tr_b16 v[154:155], v22 offset:32320
	ds_read_b64_tr_b16 v[30:31], v22 offset:32352
	v_add_f32_e32 v32, v110, v32
	s_waitcnt lgkmcnt(2)
	v_mfma_f32_16x16x32_bf16 v[74:77], v[24:27], v[18:21], v[40:43]
	v_mfma_f32_16x16x32_bf16 v[70:73], v[24:27], v[112:115], v[44:47]
	v_add_f32_e32 v24, v111, v32
	v_add_f32_e32 v24, v156, v24
	v_add_f32_e32 v24, v157, v24
	v_add_f32_e32 v24, v164, v24
	v_add_f32_e32 v24, v165, v24
	v_add_f32_e32 v24, v166, v24
	v_mfma_f32_16x16x32_bf16 v[82:85], v[62:65], v[112:115], v[36:39]
	s_nop 2
	v_add_f32_e32 v36, v167, v24
	s_waitcnt lgkmcnt(1)
	v_mfma_f32_16x16x32_bf16 v[66:69], v[152:155], v[18:21], v[48:51]
	ds_read_b64_tr_b16 v[24:25], v22 offset:27776
	ds_read_b64_tr_b16 v[26:27], v22 offset:32384
	v_mfma_f32_16x16x32_bf16 v[62:65], v[152:155], v[112:115], v[52:55]
	s_waitcnt lgkmcnt(2)
	v_mfma_f32_16x16x32_bf16 v[54:57], v[28:31], v[18:21], v[116:119]
	ds_read_b64_tr_b16 v[32:33], v22 offset:27808
	s_nop 1
	ds_read_b64_tr_b16 v[116:117], v22 offset:27840
	ds_read_b64_tr_b16 v[152:153], v22 offset:27872
	ds_read_b64_tr_b16 v[34:35], v22 offset:32416
	ds_read_b64_tr_b16 v[118:119], v22 offset:32448
	ds_read_b64_tr_b16 v[154:155], v22 offset:32480
	v_add_f32_e32 v22, v183, v36
	v_pk_add_f32 v[166:167], v[22:23], 0 op_sel_hi:[1,0]
	v_add_f32_e32 v22, 0, v202
	v_add_f32_e32 v22, v203, v22
	v_add_f32_e32 v22, v212, v22
	v_add_f32_e32 v22, v213, v22
	v_add_f32_e32 v22, v214, v22
	v_add_f32_e32 v22, v215, v22
	v_add_f32_e32 v22, v216, v22
	v_add_f32_e32 v22, v217, v22
	v_add_f32_e32 v22, v218, v22
	v_add_f32_e32 v22, v219, v22
	v_add_f32_e32 v22, v220, v22
	v_add_f32_e32 v22, v221, v22
	v_add_f32_e32 v22, v222, v22
	v_add_f32_e32 v22, v223, v22
	v_add_f32_e32 v108, v224, v22
	v_mfma_f32_16x16x32_bf16 v[50:53], v[28:31], v[112:115], v[120:123]
	v_add_f32_e32 v108, v225, v108
	v_pk_add_f32 v[164:165], v[108:109], 0 op_sel_hi:[1,0]
	v_xor_b32_e32 v106, 0x80000000, v167
	s_waitcnt lgkmcnt(6)
	v_mfma_f32_16x16x32_bf16 v[46:49], v[24:27], v[18:21], v[124:127]
	v_xor_b32_e32 v110, 0x80000000, v165
	v_lshlrev_b32_e32 v183, 1, v107
	v_mov_b32_e32 v111, v110
	v_mfma_f32_16x16x32_bf16 v[42:45], v[24:27], v[112:115], v[128:131]
	v_mov_b32_e32 v107, v106
	v_mov_b32_e32 v108, v106
	v_mov_b32_e32 v109, v106
	s_waitcnt lgkmcnt(2)
	v_mfma_f32_16x16x32_bf16 v[38:41], v[32:35], v[18:21], v[132:135]
	s_waitcnt lgkmcnt(0)
	s_barrier
	v_mfma_f32_16x16x32_bf16 v[34:37], v[32:35], v[112:115], v[136:139]
	v_mfma_f32_16x16x32_bf16 v[30:33], v[116:119], v[18:21], v[140:143]
	v_mfma_f32_16x16x32_bf16 v[26:29], v[116:119], v[112:115], v[144:147]
	v_mfma_f32_16x16x32_bf16 v[22:25], v[152:155], v[18:21], v[148:151]
	v_mfma_f32_16x16x32_bf16 v[18:21], v[152:155], v[112:115], v[168:171]
	v_mov_b32_e32 v112, v110
	v_mov_b32_e32 v113, v110
	s_nop 0
	v_lshl_add_u64 v[168:169], s[4:5], 0, v[58:59]
	v_mad_i64_i32 v[58:59], s[8:9], s14, v192, v[94:95]
	v_lshl_add_u64 v[58:59], v[58:59], 0, v[96:97]
	v_lshl_add_u64 v[170:171], s[4:5], 0, v[58:59]
	s_mov_b64 s[8:9], 0
	s_mov_b32 s34, 0x1810c000
	v_add_co_u32_e32 v236, vcc, s34, v168
	s_nop 1
	v_addc_co_u32_e32 v237, vcc, 0, v169, vcc
	v_add_co_u32_e32 v238, vcc, s34, v170
	s_nop 1
	v_addc_co_u32_e32 v239, vcc, 0, v171, vcc
	s_mov_b32 s34, 0x1930c000
	v_add_co_u32_e32 v240, vcc, s34, v168
	s_nop 1
	v_addc_co_u32_e32 v241, vcc, 0, v169, vcc
	v_add_co_u32_e32 v242, vcc, s34, v170
	s_nop 1
	v_addc_co_u32_e32 v243, vcc, 0, v171, vcc
	s_mov_b64 s[34:35], 0x4000
	s_branch .LBB0_125
; __device__ __forceinline__ unsigned cvt_pk_bf16(float lo, float hi) { unsigned r; asm volatile("v_cvt_pk_bf16_f32 %0, %1, %2" : "=v"(r) : "v"(lo), "v"(hi)); return r; }
; __device__ __forceinline__ float fmax2(float a, float b) { return __builtin_amdgcn_fmed3f(a, b, 3.0e38f); }
; template <int NMAP, int VD, bool SWA> ...
;     ...
;         for (int mp = 0; mp < NMAP; ++mp) mx[mp] = fmax2(mx[mp], __shfl_xor(mx[mp], 16));
; #pragma unroll
;         for (int mp = 0; mp < NMAP; ++mp) mx[mp] = fmax2(mx[mp], __shfl_xor(mx[mp], 32));
; #pragma unroll
;         for (int mp = 0; mp < NMAP; ++mp) {
;             if (i == 0 || __builtin_amdgcn_ballot_w64(mx[mp] > 8.0f) != 0ull) {
;                 const float delta = (i == 0) ? mx[mp] : fmaxf(mx[mp], 0.f), alpha = (i == 0) ? 0.f : __builtin_amdgcn_exp2f(-delta);
;                 mrun[mp] += delta; negm[mp] = (f32x4){-mrun[mp], -mrun[mp], -mrun[mp], -mrun[mp]}; lsum[mp] *= alpha;
; #pragma unroll
;                 for (int kt = 0; kt < 4; ++kt) sacc[mp][kt] = sacc[mp][kt] - delta;
; #pragma unroll
;                 for (int et = 0; et < NET; ++et) oacc[mp][et] = oacc[mp][et] * alpha;
;             }
;             float ps = 0.f;
; #pragma unroll
;             for (int kt = 0; kt < 4; ++kt)
; #pragma unroll
;                 for (int r = 0; r < 4; ++r) { const float p = __builtin_amdgcn_exp2f(sacc[mp][kt][r]); sacc[mp][kt][r] = p; ps += p; }
;             lsum[mp] += ps;
; #pragma unroll
;             for (int s2 = 0; s2 < 2; ++s2) {
;                 u32x4 pk; pk.x = cvt_pk_bf16(sacc[mp][2 * s2][0], sacc[mp][2 * s2][1]); pk.y = cvt_pk_bf16(sacc[mp][2 * s2][2], sacc[mp][2 * s2][3]);
;                 pk.z = cvt_pk_bf16(sacc[mp][2 * s2 + 1][0], sacc[mp][2 * s2 + 1][1]); pk.w = cvt_pk_bf16(sacc[mp][2 * s2 + 1][2], sacc[mp][2 * s2 + 1][3]);
;                 pf[mp][s2] = __builtin_bit_cast(bf16x8, pk);
;             }
;         }
; #pragma unroll
;         for (int idx = 0; idx < 2 * NET; ++idx) {
;             const int et = idx % NET, s2 = idx / NET;
;             const bf16x8 cur = va[idx & 3];
;             if (idx + 4 < 2 * NET) ATT_LDV(va[idx & 3], idx + 4);
; #pragma unroll
;             for (int mp = 0; mp < NMAP; ++mp) oacc[mp][et] = __builtin_amdgcn_mfma_f32_16x16x32_bf16(cur, pf[mp][s2], oacc[mp][et], 0, 0, 0);
;         }
.LBB0_123:
	ds_bpermute_b32 v94, v179, v225
	s_waitcnt lgkmcnt(0)
	v_max_f32_e32 v225, v225, v94
	ds_bpermute_b32 v94, v180, v225
	s_waitcnt lgkmcnt(0)
	v_max_f32_e32 v225, v225, v94
	v_max_f32_e32 v94, v225, v225
	v_max_f32_e32 v97, 0, v94
	v_exp_f32_e64 v96, -v97
	v_sub_f32_e32 v142, v142, v97
	v_sub_f32_e32 v143, v143, v97
	v_sub_f32_e32 v144, v144, v97
	v_pk_add_f32 v[94:95], v[164:165], v[96:97]
	v_pk_mul_f32 v[164:165], v[164:165], v[96:97]
	v_xor_b32_e32 v94, 0x80000000, v95
	v_mov_b32_e32 v165, v95
	v_sub_f32_e32 v145, v145, v97
	v_sub_f32_e32 v138, v138, v97
	v_sub_f32_e32 v139, v139, v97
	v_sub_f32_e32 v140, v140, v97
	v_sub_f32_e32 v141, v141, v97
	v_sub_f32_e32 v118, v118, v97
	v_sub_f32_e32 v119, v119, v97
	v_sub_f32_e32 v120, v120, v97
	v_sub_f32_e32 v121, v121, v97
	v_sub_f32_e32 v114, v114, v97
	v_sub_f32_e32 v115, v115, v97
	v_sub_f32_e32 v116, v116, v97
	v_sub_f32_e32 v117, v117, v97
	v_pk_mul_f32 v[84:85], v[84:85], v[96:97] op_sel_hi:[1,0]
	v_pk_mul_f32 v[82:83], v[82:83], v[96:97] op_sel_hi:[1,0]
	v_pk_mul_f32 v[72:73], v[72:73], v[96:97] op_sel_hi:[1,0]
	v_pk_mul_f32 v[70:71], v[70:71], v[96:97] op_sel_hi:[1,0]
	v_pk_mul_f32 v[64:65], v[64:65], v[96:97] op_sel_hi:[1,0]
	v_pk_mul_f32 v[62:63], v[62:63], v[96:97] op_sel_hi:[1,0]
	v_pk_mul_f32 v[52:53], v[52:53], v[96:97] op_sel_hi:[1,0]
	v_pk_mul_f32 v[50:51], v[50:51], v[96:97] op_sel_hi:[1,0]
	v_pk_mul_f32 v[44:45], v[44:45], v[96:97] op_sel_hi:[1,0]
	v_pk_mul_f32 v[42:43], v[42:43], v[96:97] op_sel_hi:[1,0]
	v_pk_mul_f32 v[36:37], v[36:37], v[96:97] op_sel_hi:[1,0]
	v_pk_mul_f32 v[34:35], v[34:35], v[96:97] op_sel_hi:[1,0]
	v_pk_mul_f32 v[28:29], v[28:29], v[96:97] op_sel_hi:[1,0]
	v_pk_mul_f32 v[26:27], v[26:27], v[96:97] op_sel_hi:[1,0]
	v_pk_mul_f32 v[20:21], v[20:21], v[96:97] op_sel_hi:[1,0]
	v_pk_mul_f32 v[18:19], v[18:19], v[96:97] op_sel_hi:[1,0]
	v_mov_b32_e32 v95, v94
	v_mov_b32_e32 v96, v94
	v_mov_b32_e32 v97, v94
	v_mov_b32_e32 v110, v94
	v_mov_b32_e32 v111, v94
	v_mov_b32_e32 v112, v94
	v_mov_b32_e32 v113, v94
.LBB0_124:
	v_exp_f32_e32 v142, v142
	v_exp_f32_e32 v143, v143
	v_exp_f32_e32 v144, v144
	v_exp_f32_e32 v145, v145
	v_exp_f32_e32 v202, v138
	v_exp_f32_e32 v203, v139
	v_exp_f32_e32 v225, v140
	v_exp_f32_e32 v226, v141
	v_cvt_pk_bf16_f32 v138, v142, v143
	v_cvt_pk_bf16_f32 v139, v144, v145
	v_cvt_pk_bf16_f32 v140, v202, v203
	v_cvt_pk_bf16_f32 v141, v225, v226
	v_exp_f32_e32 v227, v118
	v_exp_f32_e32 v228, v119
	v_exp_f32_e32 v229, v120
	v_exp_f32_e32 v230, v121
	v_exp_f32_e32 v231, v114
	v_exp_f32_e32 v232, v115
	v_exp_f32_e32 v233, v116
	v_exp_f32_e32 v234, v117
	v_cvt_pk_bf16_f32 v114, v227, v228
	v_cvt_pk_bf16_f32 v115, v229, v230
	v_cvt_pk_bf16_f32 v116, v231, v232
	v_cvt_pk_bf16_f32 v117, v233, v234
	ds_read_b64_tr_b16 v[120:121], v212 offset:23168
	ds_read_b64_tr_b16 v[118:119], v212 offset:18560
	v_mfma_f32_16x16x32_bf16 v[54:57], v[122:125], v[150:153], v[54:57]
	s_add_u32 s8, s8, 0x4000
	s_cmp_lg_u32 s11, s8
	v_mfma_f32_16x16x32_bf16 v[50:53], v[122:125], v[138:141], v[50:53]
	ds_read_b64_tr_b16 v[122:123], v212 offset:18592
	ds_read_b64_tr_b16 v[124:125], v212 offset:23200
	s_waitcnt lgkmcnt(2)
	v_mfma_f32_16x16x32_bf16 v[46:49], v[118:121], v[150:153], v[46:49]
	v_mfma_f32_16x16x32_bf16 v[42:45], v[118:121], v[138:141], v[42:45]
	ds_read_b64_tr_b16 v[118:119], v212 offset:18624
	s_waitcnt lgkmcnt(1)
	v_mfma_f32_16x16x32_bf16 v[38:41], v[122:125], v[150:153], v[38:41]
	v_mfma_f32_16x16x32_bf16 v[34:37], v[122:125], v[138:141], v[34:37]
	ds_read_b64_tr_b16 v[120:121], v212 offset:23232
	ds_read_b64_tr_b16 v[122:123], v212 offset:18656
	ds_read_b64_tr_b16 v[124:125], v212 offset:23264
	v_mfma_f32_16x16x32_bf16 v[66:69], v[126:129], v[150:153], v[66:69]
	v_mfma_f32_16x16x32_bf16 v[62:65], v[126:129], v[138:141], v[62:65]
	v_add_f32_e32 v223, v223, v224
	s_waitcnt lgkmcnt(2)
	v_mfma_f32_16x16x32_bf16 v[30:33], v[118:121], v[150:153], v[30:33]
	v_mfma_f32_16x16x32_bf16 v[26:29], v[118:121], v[138:141], v[26:29]
	ds_read_b64_tr_b16 v[118:119], v212 offset:27648
	ds_read_b64_tr_b16 v[120:121], v212 offset:32256
	v_mfma_f32_16x16x32_bf16 v[78:81], v[134:137], v[150:153], v[78:81]
	v_mfma_f32_16x16x32_bf16 v[82:85], v[134:137], v[138:141], v[82:85]
	s_waitcnt lgkmcnt(2)
	v_mfma_f32_16x16x32_bf16 v[22:25], v[122:125], v[150:153], v[22:25]
	v_mfma_f32_16x16x32_bf16 v[18:21], v[122:125], v[138:141], v[18:21]
	v_add_f32_e32 v122, v220, v223
	v_add_f32_e32 v122, v221, v122
	v_add_f32_e32 v122, v222, v122
	s_waitcnt lgkmcnt(0)
	v_mfma_f32_16x16x32_bf16 v[78:81], v[118:121], v[146:149], v[78:81]
	v_mfma_f32_16x16x32_bf16 v[82:85], v[118:121], v[114:117], v[82:85]
	v_add_f32_e32 v118, v217, v122
	v_add_f32_e32 v118, v218, v118
	v_add_f32_e32 v118, v219, v118
	v_add_f32_e32 v118, v214, v118
	v_add_f32_e32 v118, v215, v118
	v_add_f32_e32 v118, v216, v118
	v_add_f32_e32 v118, v156, v118
	v_add_f32_e32 v118, v157, v118
	v_mfma_f32_16x16x32_bf16 v[74:77], v[130:133], v[150:153], v[74:77]
	v_add_f32_e32 v118, v213, v118
	v_add_f32_e32 v118, v154, v118
	v_add_f32_e32 v118, v155, v118
	v_mfma_f32_16x16x32_bf16 v[70:73], v[130:133], v[138:141], v[70:73]
	ds_read_b64_tr_b16 v[126:127], v212 offset:27680
	ds_read_b64_tr_b16 v[130:131], v212 offset:27712
	ds_read_b64_tr_b16 v[134:135], v212 offset:27744
	ds_read_b64_tr_b16 v[128:129], v212 offset:32288
	ds_read_b64_tr_b16 v[132:133], v212 offset:32320
	ds_read_b64_tr_b16 v[136:137], v212 offset:32352
	v_add_f32_e32 v166, v166, v118
	ds_read_b64_tr_b16 v[118:119], v212 offset:27776
	ds_read_b64_tr_b16 v[120:121], v212 offset:32384
	s_waitcnt lgkmcnt(2)
; #define LAS __attribute__((address_space(3)))
; template <int NMAP, int VD, bool SWA> ...
;     ...
;     for (int i = 0; i < ntiles; ++i) {
;         const int t = ATT_TILE(i);
;         if (i + 1 < ntiles) { ATT_STORE((i + 1) & 1); if (i + 2 < ntiles) ATT_LOAD(ATT_TILE(i + 2)); }
;         const LAS bf16_t* kS = (const LAS bf16_t*)(lds + (i & 1) * BUFB);
;         const LAS bf16_t* vS = (const LAS bf16_t*)(lds + (i & 1) * BUFB + KBYTES);
;         bf16x8 pf[NMAP][2];
;         f32x4 sacc[NMAP][4];
; #pragma unroll
;         for (int mp = 0; mp < NMAP; ++mp) {
;             bf16x8 kf[4][2];
; #pragma unroll
;             for (int kt = 0; kt < 4; ++kt)
; #pragma unroll
;                 for (int ks = 0; ks < 2; ++ks) kf[kt][ks] = *(const LAS bf16x8*)(kS + (16 * kt + fr) * KP + mp * KMS + ks * 32 + fq * 8);
;             __builtin_amdgcn_sched_barrier(0);
; #pragma unroll
;             for (int kt = 0; kt < 4; ++kt) sacc[mp][kt] = __builtin_amdgcn_mfma_f32_16x16x32_bf16(kf[kt][0], qf[mp][0], negm[mp], 0, 0, 0);
; #pragma unroll
;             for (int kt = 0; kt < 4; ++kt) sacc[mp][kt] = __builtin_amdgcn_mfma_f32_16x16x32_bf16(kf[kt][1], qf[mp][1], sacc[mp][kt], 0, 0, 0);
;         }
;         bf16x8 va[4];
;     ...
; #pragma unroll
;         for (int i2 = 0; i2 < 4; ++i2) ATT_LDV(va[i2], i2);
;         if (SWA && t >= 4) {
;             const int dq = qp0 + 16 * w + fr - (64 * (t - 4) + 4 * fq);
; #pragma unroll
;             for (int kt = 0; kt < 4; ++kt)
; #pragma unroll
;                 for (int r = 0; r < 4; ++r) { const int d = dq - 16 * kt - r; if (d > 128 || d < -128) {
; #pragma unroll
;                     for (int mp = 0; mp < NMAP; ++mp) sacc[mp][kt][r] = -INFINITY; } }
;         }
;         float mx[NMAP];
; #pragma unroll
;         for (int mp = 0; mp < NMAP; ++mp) {
;             float v = fmax2(fmax2(sacc[mp][0][0], sacc[mp][0][1]), fmax2(sacc[mp][0][2], sacc[mp][0][3]));
; #pragma unroll
;     ...
; #pragma unroll
;         for (int idx = 0; idx < 2 * NET; ++idx) {
;             const int et = idx % NET, s2 = idx / NET;
;             const bf16x8 cur = va[idx & 3];
;             if (idx + 4 < 2 * NET) ATT_LDV(va[idx & 3], idx + 4);
; #pragma unroll
;             for (int mp = 0; mp < NMAP; ++mp) oacc[mp][et] = __builtin_amdgcn_mfma_f32_16x16x32_bf16(cur, pf[mp][s2], oacc[mp][et], 0, 0, 0);
;         }
;     ...
;         __syncthreads();
	v_mfma_f32_16x16x32_bf16 v[54:57], v[134:137], v[146:149], v[54:57]
	v_mfma_f32_16x16x32_bf16 v[50:53], v[134:137], v[114:117], v[50:53]
	v_add_f32_e32 v134, v143, v142
	v_add_f32_e32 v134, v144, v134
	v_add_f32_e32 v134, v145, v134
	s_waitcnt lgkmcnt(0)
	v_mfma_f32_16x16x32_bf16 v[46:49], v[118:121], v[146:149], v[46:49]
	v_mfma_f32_16x16x32_bf16 v[42:45], v[118:121], v[114:117], v[42:45]
	v_add_f32_e32 v118, v202, v134
	v_add_f32_e32 v118, v203, v118
	v_add_f32_e32 v118, v225, v118
	v_add_f32_e32 v118, v226, v118
	v_mfma_f32_16x16x32_bf16 v[74:77], v[126:129], v[146:149], v[74:77]
	v_add_f32_e32 v118, v227, v118
	v_add_f32_e32 v118, v228, v118
	v_add_f32_e32 v118, v229, v118
	v_mfma_f32_16x16x32_bf16 v[70:73], v[126:129], v[114:117], v[70:73]
	v_add_f32_e32 v118, v230, v118
	v_add_f32_e32 v118, v231, v118
	v_add_f32_e32 v118, v232, v118
	v_mfma_f32_16x16x32_bf16 v[66:69], v[130:133], v[146:149], v[66:69]
	v_add_f32_e32 v118, v233, v118
	v_add_f32_e32 v118, v234, v118
	v_add_f32_e32 v164, v164, v118
	v_mfma_f32_16x16x32_bf16 v[62:65], v[130:133], v[114:117], v[62:65]
	ds_read_b64_tr_b16 v[122:123], v212 offset:27808
	ds_read_b64_tr_b16 v[126:127], v212 offset:27840
	ds_read_b64_tr_b16 v[130:131], v212 offset:27872
	ds_read_b64_tr_b16 v[124:125], v212 offset:32416
	ds_read_b64_tr_b16 v[128:129], v212 offset:32448
	ds_read_b64_tr_b16 v[132:133], v212 offset:32480
	s_waitcnt lgkmcnt(0)
	v_mfma_f32_16x16x32_bf16 v[38:41], v[122:125], v[146:149], v[38:41]
	s_barrier
	v_mfma_f32_16x16x32_bf16 v[34:37], v[122:125], v[114:117], v[34:37]
	v_mfma_f32_16x16x32_bf16 v[30:33], v[126:129], v[146:149], v[30:33]
	v_mfma_f32_16x16x32_bf16 v[26:29], v[126:129], v[114:117], v[26:29]
	v_mfma_f32_16x16x32_bf16 v[22:25], v[130:133], v[146:149], v[22:25]
	v_mfma_f32_16x16x32_bf16 v[18:21], v[130:133], v[114:117], v[18:21]
	s_cbranch_scc0 .LBB0_130
.LBB0_125:
	s_mov_b32 s15, s3
	s_add_i32 s3, s3, 1
	s_bitcmp1_b32 s3, 0
	s_cselect_b32 s14, 0x9000, 0
	v_add3_u32 v58, s14, v208, v209
	v_add3_u32 v59, s14, v210, v211
	s_waitcnt vmcnt(0)
	ds_write_b128 v58, v[86:89]
	ds_write_b128 v59, v[90:93]
	ds_write_b128 v58, v[98:101] offset:18432
	ds_write_b128 v59, v[102:105] offset:18432
	global_load_dwordx4 v[86:89], v[236:237], off
	global_load_dwordx4 v[90:93], v[238:239], off
	global_load_dwordx4 v[98:101], v[240:241], off
	global_load_dwordx4 v[102:105], v[242:243], off
	v_lshl_add_u64 v[236:237], v[236:237], 0, s[34:35]
	v_lshl_add_u64 v[238:239], v[238:239], 0, s[34:35]
	v_lshl_add_u64 v[240:241], v[240:241], 0, s[34:35]
	v_lshl_add_u64 v[242:243], v[242:243], 0, s[34:35]
	s_bitcmp1_b32 s15, 0
	s_cselect_b32 s15, 0x9000, 0
	v_add3_u32 v138, s15, v183, v182
	ds_read_b128 v[58:61], v138
	ds_read_b128 v[94:97], v138 offset:64
	ds_read_b128 v[114:117], v138 offset:4608
	ds_read_b128 v[118:121], v138 offset:4672
	ds_read_b128 v[122:125], v138 offset:9216
	ds_read_b128 v[126:129], v138 offset:9280
	ds_read_b128 v[130:133], v138 offset:13824
	ds_read_b128 v[134:137], v138 offset:13888
	s_waitcnt lgkmcnt(1)
	v_mfma_f32_16x16x32_bf16 v[58:61], v[58:61], v[14:17], v[106:109]
	v_mfma_f32_16x16x32_bf16 v[114:117], v[114:117], v[14:17], v[106:109]
	v_mfma_f32_16x16x32_bf16 v[122:125], v[122:125], v[14:17], v[106:109]
	v_mfma_f32_16x16x32_bf16 v[130:133], v[130:133], v[14:17], v[106:109]
	v_mfma_f32_16x16x32_bf16 v[154:157], v[94:97], v[10:13], v[58:61]
	v_mfma_f32_16x16x32_bf16 v[150:153], v[118:121], v[10:13], v[114:117]
	v_mfma_f32_16x16x32_bf16 v[146:149], v[126:129], v[10:13], v[122:125]
	s_waitcnt lgkmcnt(0)
	v_mfma_f32_16x16x32_bf16 v[94:97], v[134:137], v[10:13], v[130:133]
	ds_read_b128 v[58:61], v138 offset:128
	ds_read_b128 v[114:117], v138 offset:192
	ds_read_b128 v[118:121], v138 offset:4736
	ds_read_b128 v[122:125], v138 offset:4800
	ds_read_b128 v[126:129], v138 offset:9344
	ds_read_b128 v[130:133], v138 offset:9408
	ds_read_b128 v[134:137], v138 offset:13952
	ds_read_b128 v[212:215], v138 offset:14016
	s_waitcnt lgkmcnt(1)
	v_mfma_f32_16x16x32_bf16 v[58:61], v[58:61], v[6:9], v[110:113]
	v_mfma_f32_16x16x32_bf16 v[118:121], v[118:121], v[6:9], v[110:113]
	v_mfma_f32_16x16x32_bf16 v[142:145], v[114:117], v[2:5], v[58:61]
	v_max3_f32 v235, v154, v155, v156
	v_max3_f32 v235, v235, v157, v150
	v_max3_f32 v235, v235, v151, v152
	v_mfma_f32_16x16x32_bf16 v[126:129], v[126:129], v[6:9], v[110:113]
	v_max3_f32 v235, v235, v153, v146
	v_max3_f32 v235, v235, v147, v148
	v_mfma_f32_16x16x32_bf16 v[134:137], v[134:137], v[6:9], v[110:113]
	v_max3_f32 v235, v235, v149, v94
	v_max3_f32 v235, v235, v95, v96
	v_mfma_f32_16x16x32_bf16 v[138:141], v[122:125], v[2:5], v[118:121]
	v_max_f32_e32 v235, v235, v97
	v_mfma_f32_16x16x32_bf16 v[118:121], v[130:133], v[2:5], v[126:129]
	v_max3_f32 v59, v142, v143, v144
	s_waitcnt lgkmcnt(0)
	v_mfma_f32_16x16x32_bf16 v[114:117], v[212:215], v[2:5], v[134:137]
	v_add3_u32 v212, s15, v0, v181
	ds_read_b64_tr_b16 v[134:135], v212 offset:18432
	ds_read_b64_tr_b16 v[130:131], v212 offset:18464
	ds_read_b64_tr_b16 v[136:137], v212 offset:23040
	ds_read_b64_tr_b16 v[132:133], v212 offset:23072
	ds_read_b64_tr_b16 v[126:127], v212 offset:18496
	ds_read_b64_tr_b16 v[128:129], v212 offset:23104
	ds_read_b64_tr_b16 v[122:123], v212 offset:18528
	ds_read_b64_tr_b16 v[124:125], v212 offset:23136
	v_max3_f32 v59, v59, v145, v138
	v_max3_f32 v59, v59, v139, v140
	v_max3_f32 v59, v59, v141, v118
	v_max3_f32 v59, v59, v119, v120
	v_max3_f32 v59, v59, v121, v114
	v_max3_f32 v59, v59, v115, v116
	v_max_f32_e32 v225, v59, v117
	v_cmp_lt_f32_e32 vcc, s72, v235
	s_cbranch_vccz .LBB0_127
; __device__ __forceinline__ unsigned cvt_pk_bf16(float lo, float hi) { unsigned r; asm volatile("v_cvt_pk_bf16_f32 %0, %1, %2" : "=v"(r) : "v"(lo), "v"(hi)); return r; }
; __device__ __forceinline__ float fmax2(float a, float b) { return __builtin_amdgcn_fmed3f(a, b, 3.0e38f); }
; template <int NMAP, int VD, bool SWA> ...
;     ...
;         for (int mp = 0; mp < NMAP; ++mp) mx[mp] = fmax2(mx[mp], __shfl_xor(mx[mp], 16));
; #pragma unroll
;         for (int mp = 0; mp < NMAP; ++mp) mx[mp] = fmax2(mx[mp], __shfl_xor(mx[mp], 32));
; #pragma unroll
;         for (int mp = 0; mp < NMAP; ++mp) {
;             if (i == 0 || __builtin_amdgcn_ballot_w64(mx[mp] > 8.0f) != 0ull) {
;                 const float delta = (i == 0) ? mx[mp] : fmaxf(mx[mp], 0.f), alpha = (i == 0) ? 0.f : __builtin_amdgcn_exp2f(-delta);
;                 mrun[mp] += delta; negm[mp] = (f32x4){-mrun[mp], -mrun[mp], -mrun[mp], -mrun[mp]}; lsum[mp] *= alpha;
; #pragma unroll
;                 for (int kt = 0; kt < 4; ++kt) sacc[mp][kt] = sacc[mp][kt] - delta;
; #pragma unroll
;                 for (int et = 0; et < NET; ++et) oacc[mp][et] = oacc[mp][et] * alpha;
;             }
;             float ps = 0.f;
; #pragma unroll
;             for (int kt = 0; kt < 4; ++kt)
; #pragma unroll
;                 for (int r = 0; r < 4; ++r) { const float p = __builtin_amdgcn_exp2f(sacc[mp][kt][r]); sacc[mp][kt][r] = p; ps += p; }
;             lsum[mp] += ps;
; #pragma unroll
;             for (int s2 = 0; s2 < 2; ++s2) {
;                 u32x4 pk; pk.x = cvt_pk_bf16(sacc[mp][2 * s2][0], sacc[mp][2 * s2][1]); pk.y = cvt_pk_bf16(sacc[mp][2 * s2][2], sacc[mp][2 * s2][3]);
;                 pk.z = cvt_pk_bf16(sacc[mp][2 * s2 + 1][0], sacc[mp][2 * s2 + 1][1]); pk.w = cvt_pk_bf16(sacc[mp][2 * s2 + 1][2], sacc[mp][2 * s2 + 1][3]);
;                 pf[mp][s2] = __builtin_bit_cast(bf16x8, pk);
;             }
	ds_bpermute_b32 v60, v179, v235
	s_waitcnt lgkmcnt(0)
	v_max_f32_e32 v58, v235, v60
	ds_bpermute_b32 v60, v180, v58
	s_waitcnt lgkmcnt(0)
	v_max_f32_e32 v58, v58, v60
	v_max_f32_e32 v58, v58, v58
	v_max_f32_e32 v61, 0, v58
	v_exp_f32_e64 v60, -v61
	v_sub_f32_e32 v154, v154, v61
	v_sub_f32_e32 v155, v155, v61
	v_sub_f32_e32 v156, v156, v61
	v_pk_add_f32 v[58:59], v[166:167], v[60:61]
	v_pk_mul_f32 v[166:167], v[166:167], v[60:61]
	v_xor_b32_e32 v58, 0x80000000, v59
	v_mov_b32_e32 v167, v59
	v_sub_f32_e32 v157, v157, v61
	v_sub_f32_e32 v150, v150, v61
	v_sub_f32_e32 v151, v151, v61
	v_sub_f32_e32 v152, v152, v61
	v_sub_f32_e32 v153, v153, v61
	v_sub_f32_e32 v146, v146, v61
	v_sub_f32_e32 v147, v147, v61
	v_sub_f32_e32 v148, v148, v61
	v_sub_f32_e32 v149, v149, v61
	v_sub_f32_e32 v94, v94, v61
	v_sub_f32_e32 v95, v95, v61
	v_sub_f32_e32 v96, v96, v61
	v_sub_f32_e32 v97, v97, v61
	v_pk_mul_f32 v[80:81], v[80:81], v[60:61] op_sel_hi:[1,0]
	v_pk_mul_f32 v[78:79], v[78:79], v[60:61] op_sel_hi:[1,0]
	v_pk_mul_f32 v[76:77], v[76:77], v[60:61] op_sel_hi:[1,0]
	v_pk_mul_f32 v[74:75], v[74:75], v[60:61] op_sel_hi:[1,0]
	v_pk_mul_f32 v[68:69], v[68:69], v[60:61] op_sel_hi:[1,0]
	v_pk_mul_f32 v[66:67], v[66:67], v[60:61] op_sel_hi:[1,0]
	v_pk_mul_f32 v[56:57], v[56:57], v[60:61] op_sel_hi:[1,0]
	v_pk_mul_f32 v[54:55], v[54:55], v[60:61] op_sel_hi:[1,0]
	v_pk_mul_f32 v[48:49], v[48:49], v[60:61] op_sel_hi:[1,0]
	v_pk_mul_f32 v[46:47], v[46:47], v[60:61] op_sel_hi:[1,0]
	v_pk_mul_f32 v[40:41], v[40:41], v[60:61] op_sel_hi:[1,0]
	v_pk_mul_f32 v[38:39], v[38:39], v[60:61] op_sel_hi:[1,0]
	v_pk_mul_f32 v[32:33], v[32:33], v[60:61] op_sel_hi:[1,0]
	v_pk_mul_f32 v[30:31], v[30:31], v[60:61] op_sel_hi:[1,0]
	v_pk_mul_f32 v[24:25], v[24:25], v[60:61] op_sel_hi:[1,0]
	v_pk_mul_f32 v[22:23], v[22:23], v[60:61] op_sel_hi:[1,0]
	v_mov_b32_e32 v59, v58
	v_mov_b32_e32 v60, v58
	v_mov_b32_e32 v61, v58
	v_mov_b32_e32 v106, v58
	v_mov_b32_e32 v107, v58
	v_mov_b32_e32 v108, v58
	v_mov_b32_e32 v109, v58
	s_branch .LBB0_128
.LBB0_127:
.LBB0_128:
	s_waitcnt lgkmcnt(0)
	v_exp_f32_e32 v224, v154
	v_exp_f32_e32 v223, v155
	v_exp_f32_e32 v220, v156
	v_exp_f32_e32 v221, v157
	v_exp_f32_e32 v222, v150
	v_exp_f32_e32 v217, v151
	v_exp_f32_e32 v218, v152
	v_exp_f32_e32 v219, v153
	v_exp_f32_e32 v214, v146
	v_exp_f32_e32 v215, v147
	v_exp_f32_e32 v216, v148
	v_exp_f32_e32 v156, v149
	v_exp_f32_e32 v157, v94
	v_exp_f32_e32 v213, v95
	v_exp_f32_e32 v154, v96
	v_exp_f32_e32 v155, v97
	v_cmp_lt_f32_e32 vcc, s72, v225
	v_cvt_pk_bf16_f32 v150, v224, v223
	v_cvt_pk_bf16_f32 v151, v220, v221
	v_cvt_pk_bf16_f32 v152, v222, v217
	v_cvt_pk_bf16_f32 v153, v218, v219
	v_cvt_pk_bf16_f32 v146, v214, v215
	v_cvt_pk_bf16_f32 v147, v216, v156
	v_cvt_pk_bf16_f32 v148, v157, v213
	v_cvt_pk_bf16_f32 v149, v154, v155
	s_cbranch_vccnz .LBB0_123
	s_branch .LBB0_124
; #define LAS __attribute__((address_space(3)))
; template <int NMAP, int VD, bool SWA> ...
;     ...
;     for (int i = 0; i < ntiles; ++i) {
;         const int t = ATT_TILE(i);
;         if (i + 1 < ntiles) { ATT_STORE((i + 1) & 1); if (i + 2 < ntiles) ATT_LOAD(ATT_TILE(i + 2)); }
;         const LAS bf16_t* kS = (const LAS bf16_t*)(lds + (i & 1) * BUFB);
;         const LAS bf16_t* vS = (const LAS bf16_t*)(lds + (i & 1) * BUFB + KBYTES);
;         bf16x8 pf[NMAP][2];
;         f32x4 sacc[NMAP][4];
; #pragma unroll
;         for (int mp = 0; mp < NMAP; ++mp) {
;             bf16x8 kf[4][2];
; #pragma unroll
;             for (int kt = 0; kt < 4; ++kt)
; #pragma unroll
;                 for (int ks = 0; ks < 2; ++ks) kf[kt][ks] = *(const LAS bf16x8*)(kS + (16 * kt + fr) * KP + mp * KMS + ks * 32 + fq * 8);
;             __builtin_amdgcn_sched_barrier(0);
; #pragma unroll
;             for (int kt = 0; kt < 4; ++kt) sacc[mp][kt] = __builtin_amdgcn_mfma_f32_16x16x32_bf16(kf[kt][0], qf[mp][0], negm[mp], 0, 0, 0);
; #pragma unroll
;             for (int kt = 0; kt < 4; ++kt) sacc[mp][kt] = __builtin_amdgcn_mfma_f32_16x16x32_bf16(kf[kt][1], qf[mp][1], sacc[mp][kt], 0, 0, 0);
;         }
;         bf16x8 va[4];
;     ...
; #pragma unroll
;         for (int i2 = 0; i2 < 4; ++i2) ATT_LDV(va[i2], i2);
;         if (SWA && t >= 4) {
;             const int dq = qp0 + 16 * w + fr - (64 * (t - 4) + 4 * fq);
; #pragma unroll
;             for (int kt = 0; kt < 4; ++kt)
; #pragma unroll
;                 for (int r = 0; r < 4; ++r) { const int d = dq - 16 * kt - r; if (d > 128 || d < -128) {
; #pragma unroll
;                     for (int mp = 0; mp < NMAP; ++mp) sacc[mp][kt][r] = -INFINITY; } }
;         }
;         float mx[NMAP];
; #pragma unroll
;         for (int mp = 0; mp < NMAP; ++mp) {
;             float v = fmax2(fmax2(sacc[mp][0][0], sacc[mp][0][1]), fmax2(sacc[mp][0][2], sacc[mp][0][3]));
; #pragma unroll
;             for (int kt = 1; kt < 4; ++kt) v = fmax2(v, fmax2(fmax2(sacc[mp][kt][0], sacc[mp][kt][1]), fmax2(sacc[mp][kt][2], sacc[mp][kt][3])));
;             mx[mp] = v;
;         }
; #pragma unroll
;         for (int mp = 0; mp < NMAP; ++mp) mx[mp] = fmax2(mx[mp], __shfl_xor(mx[mp], 16));
; #pragma unroll
;         for (int mp = 0; mp < NMAP; ++mp) mx[mp] = fmax2(mx[mp], __shfl_xor(mx[mp], 32));
; #pragma unroll
;         for (int mp = 0; mp < NMAP; ++mp) {
.LBB0_130:
	v_mov_b64_e32 v[58:59], v[106:107]
	v_mov_b64_e32 v[60:61], v[108:109]
	v_mov_b64_e32 v[94:95], v[110:111]
	v_mov_b64_e32 v[96:97], v[112:113]
	s_bitcmp1_b32 s10, 0
	s_cselect_b32 s3, 0x9000, 0
	s_add_i32 s3, s3, 0
	v_add3_u32 v106, s3, v208, v209
	s_waitcnt vmcnt(3)
	ds_write_b128 v106, v[86:89]
	v_add3_u32 v86, s3, v210, v211
	s_waitcnt vmcnt(2)
	ds_write_b128 v86, v[90:93]
	s_waitcnt vmcnt(1)
	ds_write_b128 v106, v[98:101] offset:18432
	s_waitcnt vmcnt(0)
	ds_write_b128 v86, v[102:105] offset:18432
	v_add3_u32 v122, s14, v183, v182
	ds_read_b128 v[86:89], v122
	ds_read_b128 v[90:93], v122 offset:64
	ds_read_b128 v[98:101], v122 offset:4608
	ds_read_b128 v[102:105], v122 offset:4672
	ds_read_b128 v[106:109], v122 offset:9216
	ds_read_b128 v[110:113], v122 offset:9280
	ds_read_b128 v[114:117], v122 offset:13824
	ds_read_b128 v[118:121], v122 offset:13888
	s_waitcnt lgkmcnt(7)
	v_mfma_f32_16x16x32_bf16 v[86:89], v[86:89], v[14:17], v[58:61]
	s_waitcnt lgkmcnt(5)
	v_mfma_f32_16x16x32_bf16 v[98:101], v[98:101], v[14:17], v[58:61]
	s_waitcnt lgkmcnt(3)
	v_mfma_f32_16x16x32_bf16 v[106:109], v[106:109], v[14:17], v[58:61]
	s_waitcnt lgkmcnt(1)
	v_mfma_f32_16x16x32_bf16 v[114:117], v[114:117], v[14:17], v[58:61]
	v_mfma_f32_16x16x32_bf16 v[134:137], v[90:93], v[10:13], v[86:89]
	v_mfma_f32_16x16x32_bf16 v[130:133], v[102:105], v[10:13], v[98:101]
	v_mfma_f32_16x16x32_bf16 v[126:129], v[110:113], v[10:13], v[106:109]
	s_waitcnt lgkmcnt(0)
	v_mfma_f32_16x16x32_bf16 v[106:109], v[118:121], v[10:13], v[114:117]
	ds_read_b128 v[86:89], v122 offset:128
	ds_read_b128 v[90:93], v122 offset:192
	ds_read_b128 v[98:101], v122 offset:4736
	ds_read_b128 v[102:105], v122 offset:4800
	ds_read_b128 v[110:113], v122 offset:9344
	ds_read_b128 v[114:117], v122 offset:9408
	ds_read_b128 v[118:121], v122 offset:13952
	ds_read_b128 v[138:141], v122 offset:14016
	s_waitcnt lgkmcnt(3)
	v_mfma_f32_16x16x32_bf16 v[110:113], v[110:113], v[6:9], v[94:97]
	s_waitcnt lgkmcnt(1)
	v_mfma_f32_16x16x32_bf16 v[142:145], v[118:121], v[6:9], v[94:97]
	v_mfma_f32_16x16x32_bf16 v[86:89], v[86:89], v[6:9], v[94:97]
	v_mfma_f32_16x16x32_bf16 v[98:101], v[98:101], v[6:9], v[94:97]
	v_mfma_f32_16x16x32_bf16 v[114:117], v[114:117], v[2:5], v[110:113]
	s_waitcnt lgkmcnt(0)
	v_mfma_f32_16x16x32_bf16 v[110:113], v[138:141], v[2:5], v[142:145]
	v_med3_f32 v139, v134, v135, s27
	v_med3_f32 v140, v136, v137, s27
	v_med3_f32 v139, v139, v140, s27
	v_med3_f32 v140, v130, v131, s27
	v_med3_f32 v141, v132, v133, s27
	v_med3_f32 v140, v140, v141, s27
	v_mfma_f32_16x16x32_bf16 v[122:125], v[90:93], v[2:5], v[86:89]
	v_med3_f32 v139, v139, v140, s27
	v_med3_f32 v140, v126, v127, s27
	v_med3_f32 v141, v128, v129, s27
	v_mfma_f32_16x16x32_bf16 v[118:121], v[102:105], v[2:5], v[98:101]
	v_med3_f32 v140, v140, v141, s27
	v_med3_f32 v139, v139, v140, s27
	v_med3_f32 v140, v106, v107, s27
	v_med3_f32 v141, v108, v109, s27
	v_med3_f32 v140, v140, v141, s27
	v_med3_f32 v139, v139, v140, s27
	v_med3_f32 v140, v122, v123, s27
	v_med3_f32 v141, v124, v125, s27
	v_med3_f32 v140, v140, v141, s27
	v_med3_f32 v141, v118, v119, s27
	v_med3_f32 v142, v120, v121, s27
	v_med3_f32 v141, v141, v142, s27
	v_med3_f32 v140, v140, v141, s27
	v_med3_f32 v141, v114, v115, s27
	v_med3_f32 v142, v116, v117, s27
	v_med3_f32 v141, v141, v142, s27
	v_med3_f32 v140, v140, v141, s27
	v_med3_f32 v141, v110, v111, s27
	v_med3_f32 v142, v112, v113, s27
	v_med3_f32 v141, v141, v142, s27
	v_med3_f32 v140, v140, v141, s27
	ds_bpermute_b32 v141, v179, v139
	v_add3_u32 v138, s14, v0, v181
	ds_read_b64_tr_b16 v[102:103], v138 offset:18432
	ds_read_b64_tr_b16 v[98:99], v138 offset:18464
	ds_read_b64_tr_b16 v[104:105], v138 offset:23040
	ds_read_b64_tr_b16 v[100:101], v138 offset:23072
	ds_read_b64_tr_b16 v[90:91], v138 offset:18496
	ds_read_b64_tr_b16 v[92:93], v138 offset:23104
	ds_read_b64_tr_b16 v[86:87], v138 offset:18528
	ds_read_b64_tr_b16 v[88:89], v138 offset:23136
	s_waitcnt lgkmcnt(8)
	v_med3_f32 v141, v139, v141, s27
	ds_bpermute_b32 v139, v179, v140
	s_waitcnt lgkmcnt(0)
	v_med3_f32 v139, v140, v139, s27
	ds_bpermute_b32 v140, v180, v141
	s_waitcnt lgkmcnt(0)
	v_med3_f32 v141, v141, v140, s27
	ds_bpermute_b32 v140, v180, v139
	v_cmp_lt_f32_e32 vcc, s72, v141
	s_cbranch_vccz .LBB0_132
	v_max_f32_e32 v58, v141, v141
	v_max_f32_e32 v59, 0, v58
	v_exp_f32_e64 v60, -v59
	v_add_f32_e32 v58, v167, v59
	v_xor_b32_e32 v58, 0x80000000, v58
	v_sub_f32_e32 v134, v134, v59
	v_mul_f32_e32 v166, v166, v60
	v_sub_f32_e32 v135, v135, v59
	v_sub_f32_e32 v136, v136, v59
	v_sub_f32_e32 v137, v137, v59
	v_sub_f32_e32 v130, v130, v59
	v_sub_f32_e32 v131, v131, v59
	v_sub_f32_e32 v132, v132, v59
	v_sub_f32_e32 v133, v133, v59
	v_sub_f32_e32 v126, v126, v59
	v_sub_f32_e32 v127, v127, v59
	v_sub_f32_e32 v128, v128, v59
	v_sub_f32_e32 v129, v129, v59
	v_sub_f32_e32 v106, v106, v59
	v_sub_f32_e32 v107, v107, v59
	v_sub_f32_e32 v108, v108, v59
	v_sub_f32_e32 v109, v109, v59
	v_pk_mul_f32 v[80:81], v[80:81], v[60:61] op_sel_hi:[1,0]
	v_pk_mul_f32 v[78:79], v[78:79], v[60:61] op_sel_hi:[1,0]
	v_pk_mul_f32 v[76:77], v[76:77], v[60:61] op_sel_hi:[1,0]
	v_pk_mul_f32 v[74:75], v[74:75], v[60:61] op_sel_hi:[1,0]
	v_pk_mul_f32 v[68:69], v[68:69], v[60:61] op_sel_hi:[1,0]
	v_pk_mul_f32 v[66:67], v[66:67], v[60:61] op_sel_hi:[1,0]
	v_pk_mul_f32 v[56:57], v[56:57], v[60:61] op_sel_hi:[1,0]
	v_pk_mul_f32 v[54:55], v[54:55], v[60:61] op_sel_hi:[1,0]
	v_pk_mul_f32 v[48:49], v[48:49], v[60:61] op_sel_hi:[1,0]
	v_pk_mul_f32 v[46:47], v[46:47], v[60:61] op_sel_hi:[1,0]
	v_pk_mul_f32 v[40:41], v[40:41], v[60:61] op_sel_hi:[1,0]
	v_pk_mul_f32 v[38:39], v[38:39], v[60:61] op_sel_hi:[1,0]
	v_pk_mul_f32 v[32:33], v[32:33], v[60:61] op_sel_hi:[1,0]
	v_pk_mul_f32 v[30:31], v[30:31], v[60:61] op_sel_hi:[1,0]
	v_pk_mul_f32 v[24:25], v[24:25], v[60:61] op_sel_hi:[1,0]
	v_pk_mul_f32 v[22:23], v[22:23], v[60:61] op_sel_hi:[1,0]
	v_mov_b32_e32 v59, v58
	v_mov_b32_e32 v60, v58
	v_mov_b32_e32 v61, v58
